# bundle22 + the mem-row rmsnorm loop also loads its loop-invariant gain once (was 8 serialized loads per row)
# speedup vs baseline: 1.0091x; 1.0001x over previous
.LBB0_225:
	s_cmpk_gt_i32 s4, 0xfff
	s_cbranch_scc1 .LBB0_228
	v_mbcnt_lo_u32_b32 v1, -1, 0
	v_mbcnt_hi_u32_b32 v1, -1, v1
	v_and_b32_e32 v4, 64, v1
	v_add_u32_e32 v4, 64, v4
	v_xor_b32_e32 v5, 1, v1
	v_cmp_lt_i32_e32 vcc, v5, v4
	s_ashr_i32 s5, s4, 31
	s_lshl_b64 s[2:3], s[4:5], 12
	v_cndmask_b32_e32 v5, v1, v5, vcc
	v_lshlrev_b32_e32 v33, 2, v5
	v_xor_b32_e32 v5, 2, v1
	v_cmp_lt_i32_e32 vcc, v5, v4
	v_mov_b32_e32 v3, 0
	s_add_u32 s2, s26, s2
	v_cndmask_b32_e32 v5, v1, v5, vcc
	v_lshlrev_b32_e32 v34, 2, v5
	v_xor_b32_e32 v5, 4, v1
	v_cmp_lt_i32_e32 vcc, v5, v4
	v_mov_b32_e32 v19, v3
	s_addc_u32 s3, s27, s3
	v_cndmask_b32_e32 v5, v1, v5, vcc
	v_lshlrev_b32_e32 v35, 2, v5
	v_xor_b32_e32 v5, 8, v1
	v_cmp_lt_i32_e32 vcc, v5, v4
	v_lshlrev_b32_e32 v2, 4, v252
	s_ashr_i32 s7, s6, 31
	v_cndmask_b32_e32 v5, v1, v5, vcc
	v_lshlrev_b32_e32 v36, 2, v5
	v_xor_b32_e32 v5, 16, v1
	v_cmp_lt_i32_e32 vcc, v5, v4
	v_lshl_add_u64 v[20:21], s[80:81], 0, v[2:3]
	s_mov_b64 s[0:1], 0x1000
	v_cndmask_b32_e32 v5, v1, v5, vcc
	v_lshlrev_b32_e32 v37, 2, v5
	v_xor_b32_e32 v5, 32, v1
	v_cmp_lt_i32_e32 vcc, v5, v4
	s_lshl_b64 s[8:9], s[4:5], 13
	v_lshl_add_u64 v[22:23], v[20:21], 0, s[0:1]
	v_cndmask_b32_e32 v1, v1, v5, vcc
	v_lshl_add_u64 v[4:5], s[2:3], 0, v[18:19]
	s_mov_b64 s[2:3], 0x10000e00
	v_lshl_add_u64 v[18:19], v[4:5], 0, s[2:3]
	s_lshl_b64 s[2:3], s[6:7], 12
	s_mov_b64 s[0:1], 0x1400
	s_add_u32 s8, s70, s8
	v_lshl_add_u64 v[24:25], v[20:21], 0, s[0:1]
	s_mov_b64 s[0:1], 0x1800
	s_addc_u32 s9, s71, s9
	v_lshl_add_u64 v[26:27], v[20:21], 0, s[0:1]
	s_mov_b64 s[0:1], 0x1c00
	v_lshl_add_u64 v[2:3], s[8:9], 0, v[2:3]
	v_lshlrev_b32_e32 v38, 2, v1
	v_lshl_add_u64 v[28:29], v[20:21], 0, s[0:1]
	v_lshl_add_u64 v[30:31], v[2:3], 0, s[0:1]
	s_lshl_b64 s[8:9], s[6:7], 13
	v_mov_b32_e32 v39, 0x358637bd
	s_mov_b32 s5, 0xf800000
	v_mov_b32_e32 v40, 0x260
	s_movk_i32 s7, 0x7fff
	v_mov_b32_e32 v41, 1
	global_load_dwordx4 v[200:203], v[20:21], off
	global_load_dwordx4 v[204:207], v[20:21], off offset:1024
	global_load_dwordx4 v[208:211], v[20:21], off offset:2048
	global_load_dwordx4 v[212:215], v[20:21], off offset:3072
	global_load_dwordx4 v[216:219], v[22:23], off
	global_load_dwordx4 v[220:223], v[24:25], off
	global_load_dwordx4 v[224:227], v[26:27], off
	global_load_dwordx4 v[228:231], v[28:29], off
	s_waitcnt vmcnt(0)
.LBB0_227:
	global_load_dwordx4 v[14:17], v[30:31], off offset:-3072
	global_load_dwordx4 v[10:13], v[30:31], off offset:-2048
	global_load_dwordx4 v[2:5], v[30:31], off
	global_load_dwordx4 v[6:9], v[30:31], off offset:-1024
	v_add_co_u32_e32 v62, vcc, 0xfffff000, v30
	s_add_i32 s4, s4, s6
	s_nop 0
	v_addc_co_u32_e32 v63, vcc, -1, v31, vcc
	global_load_dwordx4 v[46:49], v[62:63], off offset:-3072
	global_load_dwordx4 v[50:53], v[62:63], off offset:-2048
	global_load_dwordx4 v[54:57], v[62:63], off offset:-1024
	global_load_dwordx4 v[58:61], v[30:31], off offset:-4096
	s_cmpk_gt_i32 s4, 0xfff
	v_lshl_add_u64 v[30:31], v[30:31], 0, s[8:9]
	s_nop 0
	s_waitcnt vmcnt(7)
	v_mul_f32_e32 v1, v14, v14
	s_nop 0
	s_waitcnt vmcnt(6)
	v_pk_mul_f32 v[62:63], v[12:13], v[12:13]
	v_pk_mul_f32 v[64:65], v[10:11], v[10:11]
	s_nop 0
	s_waitcnt vmcnt(4)
	v_mul_f32_e32 v32, v7, v7
	v_mul_f32_e32 v66, v9, v9
	v_mul_f32_e32 v83, v4, v4
	v_mul_f32_e32 v89, v5, v5
	s_nop 0
	v_mov_b32_e32 v68, v200
	v_mov_b32_e32 v69, v202
	v_mov_b32_e32 v44, v201
	v_pk_mov_b32 v[42:43], v[64:65], v[62:63] op_sel:[1,0]
	v_mov_b32_e32 v65, v63
	v_pk_fma_f32 v[62:63], v[6:7], v[6:7], v[32:33] op_sel_hi:[1,1,0]
	v_pk_fma_f32 v[66:67], v[8:9], v[8:9], v[66:67] op_sel_hi:[1,1,0]
	s_nop 0
	s_waitcnt vmcnt(3)
	v_mov_b32_e32 v72, v47
	s_nop 0
	s_waitcnt vmcnt(2)
	v_mov_b32_e32 v73, v51
	v_mov_b32_e32 v76, v49
	v_mov_b32_e32 v77, v53
	v_mov_b32_e32 v70, v46
	v_mov_b32_e32 v71, v50
	v_mov_b32_e32 v74, v48
	v_mov_b32_e32 v75, v52
	s_nop 0
	s_waitcnt vmcnt(1)
	v_pk_mul_f32 v[78:79], v[56:57], v[56:57]
	v_pk_mul_f32 v[80:81], v[54:55], v[54:55]
	v_pk_add_f32 v[42:43], v[42:43], v[64:65]
	v_mov_b32_e32 v63, v83
	v_mov_b32_e32 v67, v89
	v_mov_b32_e32 v64, v46
	v_mov_b32_e32 v65, v48
	v_mov_b32_e32 v48, v47
	v_mov_b32_e32 v46, v50
	v_mov_b32_e32 v47, v52
	v_mov_b32_e32 v52, v51
	v_pk_mul_f32 v[50:51], v[72:73], v[72:73]
	v_pk_mul_f32 v[72:73], v[76:77], v[76:77]
	v_pk_mov_b32 v[76:77], v[80:81], v[78:79] op_sel:[1,0]
	v_mov_b32_e32 v81, v79
	v_pk_add_f32 v[62:63], v[62:63], v[66:67]
	v_pk_fma_f32 v[50:51], v[70:71], v[70:71], v[50:51]
	v_pk_fma_f32 v[66:67], v[74:75], v[74:75], v[72:73]
	s_nop 0
	s_waitcnt vmcnt(0)
	v_mul_f32_e32 v32, v59, v59
	v_mul_f32_e32 v82, v61, v61
	v_pk_add_f32 v[70:71], v[76:77], v[80:81]
	v_pk_add_f32 v[50:51], v[50:51], v[66:67]
	v_mul_f32_e32 v84, v15, v15
	v_mul_f32_e32 v85, v16, v16
	v_mul_f32_e32 v86, v17, v17
	v_pk_fma_f32 v[78:79], v[58:59], v[58:59], v[32:33] op_sel_hi:[1,1,0]
	v_pk_fma_f32 v[82:83], v[60:61], v[60:61], v[82:83] op_sel_hi:[1,1,0]
	v_pk_add_f32 v[66:67], v[70:71], v[70:71] op_sel:[0,1] op_sel_hi:[1,0]
	v_pk_add_f32 v[50:51], v[50:51], v[50:51] op_sel:[0,1] op_sel_hi:[1,0]
	v_mov_b32_e32 v79, v85
	v_mov_b32_e32 v83, v86
	v_mov_b32_e32 v67, v84
	v_mov_b32_e32 v51, v1
	v_pk_add_f32 v[70:71], v[78:79], v[82:83]
	v_pk_add_f32 v[50:51], v[50:51], v[66:67]
	v_mul_f32_e32 v87, v2, v2
	v_pk_add_f32 v[50:51], v[50:51], v[70:71]
	v_mul_f32_e32 v88, v3, v3
	v_pk_add_f32 v[42:43], v[42:43], v[42:43] op_sel:[0,1] op_sel_hi:[1,0]
	v_pk_add_f32 v[50:51], v[50:51], v[50:51] op_sel:[0,1] op_sel_hi:[1,0]
	v_mov_b32_e32 v43, v88
	v_mov_b32_e32 v51, v87
	v_pk_add_f32 v[42:43], v[50:51], v[42:43]
	s_nop 0
	v_pk_add_f32 v[42:43], v[42:43], v[62:63]
	s_nop 0
	v_add_f32_e32 v1, v42, v43
	ds_bpermute_b32 v32, v33, v1
	s_waitcnt lgkmcnt(0)
	v_add_f32_e32 v1, v1, v32
	ds_bpermute_b32 v32, v34, v1
	s_waitcnt lgkmcnt(0)
	v_add_f32_e32 v1, v1, v32
	ds_bpermute_b32 v32, v35, v1
	s_waitcnt lgkmcnt(0)
	v_add_f32_e32 v1, v1, v32
	ds_bpermute_b32 v32, v36, v1
	s_waitcnt lgkmcnt(0)
	v_add_f32_e32 v1, v1, v32
	ds_bpermute_b32 v32, v37, v1
	s_waitcnt lgkmcnt(0)
	v_add_f32_e32 v1, v1, v32
	ds_bpermute_b32 v32, v38, v1
	s_waitcnt lgkmcnt(0)
	v_add_f32_e32 v1, v1, v32
	v_fmamk_f32 v1, v1, 0x3a000000, v39
	v_mul_f32_e32 v32, 0x4f800000, v1
	v_cmp_gt_f32_e32 vcc, s5, v1
	s_nop 1
	v_cndmask_b32_e32 v1, v1, v32, vcc
	v_sqrt_f32_e32 v32, v1
	s_nop 0
	v_add_u32_e32 v42, -1, v32
	v_add_u32_e32 v43, 1, v32
	v_fma_f32 v50, -v42, v32, v1
	v_fma_f32 v51, -v43, v32, v1
	v_cmp_ge_f32_e64 s[0:1], 0, v50
	s_nop 1
	v_cndmask_b32_e64 v32, v32, v42, s[0:1]
	v_cmp_lt_f32_e64 s[0:1], 0, v51
	s_nop 1
	v_cndmask_b32_e64 v32, v32, v43, s[0:1]
	v_mul_f32_e32 v42, 0x37800000, v32
	v_cndmask_b32_e32 v32, v32, v42, vcc
	v_cmp_class_f32_e32 vcc, v1, v40
	s_nop 1
	v_cndmask_b32_e32 v1, v32, v1, vcc
	v_div_scale_f32 v32, s[0:1], v1, v1, 1.0
	v_rcp_f32_e32 v43, v32
	v_div_scale_f32 v42, vcc, 1.0, v1, 1.0
	v_fma_f32 v50, -v32, v43, 1.0
	v_fmac_f32_e32 v43, v50, v43
	v_mul_f32_e32 v50, v42, v43
	v_fma_f32 v51, -v32, v50, v42
	v_fmac_f32_e32 v50, v51, v43
	v_fma_f32 v32, -v32, v50, v42
	v_div_fmas_f32 v32, v32, v43, v50
	v_div_fixup_f32 v32, v32, v1, 1.0
	v_pk_mul_f32 v[42:43], v[64:65], v[32:33] op_sel_hi:[1,0]
	v_pk_mul_f32 v[48:49], v[48:49], v[32:33] op_sel_hi:[1,0]
	v_pk_mul_f32 v[42:43], v[68:69], v[42:43]
	v_mov_b32_e32 v45, v203
	v_pk_mul_f32 v[44:45], v[44:45], v[48:49]
	v_and_b32_sdwa v1, v43, v41 dst_sel:DWORD dst_unused:UNUSED_PAD src0_sel:WORD_1 src1_sel:DWORD
	v_and_b32_sdwa v49, v45, v41 dst_sel:DWORD dst_unused:UNUSED_PAD src0_sel:WORD_1 src1_sel:DWORD
	v_and_b32_sdwa v50, v44, v41 dst_sel:DWORD dst_unused:UNUSED_PAD src0_sel:WORD_1 src1_sel:DWORD
	v_and_b32_sdwa v48, v42, v41 dst_sel:DWORD dst_unused:UNUSED_PAD src0_sel:WORD_1 src1_sel:DWORD
	v_add3_u32 v1, v43, v1, s7
	v_add3_u32 v43, v45, v49, s7
	v_add3_u32 v44, v44, v50, s7
	v_add3_u32 v42, v42, v48, s7
	v_and_b32_e32 v43, 0xffff0000, v43
	v_and_b32_e32 v44, 0xffff0000, v44
	v_or_b32_sdwa v43, v43, v1 dst_sel:DWORD dst_unused:UNUSED_PAD src0_sel:DWORD src1_sel:WORD_1
	v_or_b32_sdwa v42, v44, v42 dst_sel:DWORD dst_unused:UNUSED_PAD src0_sel:DWORD src1_sel:WORD_1
	global_store_dwordx2 v[18:19], v[42:43], off offset:-3584
	v_pk_mul_f32 v[46:47], v[46:47], v[32:33] op_sel_hi:[1,0]
	v_pk_mul_f32 v[48:49], v[52:53], v[32:33] op_sel_hi:[1,0]
	s_nop 0
	v_mov_b32_e32 v50, v204
	v_mov_b32_e32 v51, v206
	v_mov_b32_e32 v44, v205
	v_pk_mul_f32 v[42:43], v[50:51], v[46:47]
	v_mov_b32_e32 v45, v207
	v_pk_mul_f32 v[44:45], v[44:45], v[48:49]
	v_and_b32_sdwa v1, v43, v41 dst_sel:DWORD dst_unused:UNUSED_PAD src0_sel:WORD_1 src1_sel:DWORD
	v_and_b32_sdwa v47, v45, v41 dst_sel:DWORD dst_unused:UNUSED_PAD src0_sel:WORD_1 src1_sel:DWORD
	v_and_b32_sdwa v48, v44, v41 dst_sel:DWORD dst_unused:UNUSED_PAD src0_sel:WORD_1 src1_sel:DWORD
	v_and_b32_sdwa v46, v42, v41 dst_sel:DWORD dst_unused:UNUSED_PAD src0_sel:WORD_1 src1_sel:DWORD
	v_add3_u32 v1, v43, v1, s7
	v_add3_u32 v43, v45, v47, s7
	v_add3_u32 v44, v44, v48, s7
	v_add3_u32 v42, v42, v46, s7
	v_and_b32_e32 v43, 0xffff0000, v43
	v_and_b32_e32 v44, 0xffff0000, v44
	v_or_b32_sdwa v43, v43, v1 dst_sel:DWORD dst_unused:UNUSED_PAD src0_sel:DWORD src1_sel:WORD_1
	v_or_b32_sdwa v42, v44, v42 dst_sel:DWORD dst_unused:UNUSED_PAD src0_sel:DWORD src1_sel:WORD_1
	global_store_dwordx2 v[18:19], v[42:43], off offset:-3072
	v_mov_b32_e32 v46, v54
	v_mov_b32_e32 v47, v56
	v_mov_b32_e32 v56, v55
	v_pk_mul_f32 v[46:47], v[46:47], v[32:33] op_sel_hi:[1,0]
	v_pk_mul_f32 v[48:49], v[56:57], v[32:33] op_sel_hi:[1,0]
	s_nop 0
	v_mov_b32_e32 v50, v208
	v_mov_b32_e32 v51, v210
	v_mov_b32_e32 v44, v209
	v_pk_mul_f32 v[42:43], v[50:51], v[46:47]
	v_mov_b32_e32 v45, v211
	v_pk_mul_f32 v[44:45], v[44:45], v[48:49]
	v_and_b32_sdwa v1, v43, v41 dst_sel:DWORD dst_unused:UNUSED_PAD src0_sel:WORD_1 src1_sel:DWORD
	v_and_b32_sdwa v47, v45, v41 dst_sel:DWORD dst_unused:UNUSED_PAD src0_sel:WORD_1 src1_sel:DWORD
	v_and_b32_sdwa v48, v44, v41 dst_sel:DWORD dst_unused:UNUSED_PAD src0_sel:WORD_1 src1_sel:DWORD
	v_and_b32_sdwa v46, v42, v41 dst_sel:DWORD dst_unused:UNUSED_PAD src0_sel:WORD_1 src1_sel:DWORD
	v_add3_u32 v1, v43, v1, s7
	v_add3_u32 v43, v45, v47, s7
	v_add3_u32 v44, v44, v48, s7
	v_add3_u32 v42, v42, v46, s7
	v_and_b32_e32 v43, 0xffff0000, v43
	v_and_b32_e32 v44, 0xffff0000, v44
	v_or_b32_sdwa v43, v43, v1 dst_sel:DWORD dst_unused:UNUSED_PAD src0_sel:DWORD src1_sel:WORD_1
	v_or_b32_sdwa v42, v44, v42 dst_sel:DWORD dst_unused:UNUSED_PAD src0_sel:DWORD src1_sel:WORD_1
	global_store_dwordx2 v[18:19], v[42:43], off offset:-2560
	v_mov_b32_e32 v46, v58
	v_mov_b32_e32 v47, v60
	v_mov_b32_e32 v60, v59
	v_pk_mul_f32 v[46:47], v[46:47], v[32:33] op_sel_hi:[1,0]
	v_pk_mul_f32 v[48:49], v[60:61], v[32:33] op_sel_hi:[1,0]
	s_nop 0
	v_mov_b32_e32 v50, v212
	v_mov_b32_e32 v51, v214
	v_mov_b32_e32 v44, v213
	v_pk_mul_f32 v[42:43], v[46:47], v[50:51]
	v_mov_b32_e32 v45, v215
	v_pk_mul_f32 v[44:45], v[48:49], v[44:45]
	v_and_b32_sdwa v1, v43, v41 dst_sel:DWORD dst_unused:UNUSED_PAD src0_sel:WORD_1 src1_sel:DWORD
	v_and_b32_sdwa v47, v45, v41 dst_sel:DWORD dst_unused:UNUSED_PAD src0_sel:WORD_1 src1_sel:DWORD
	v_and_b32_sdwa v48, v44, v41 dst_sel:DWORD dst_unused:UNUSED_PAD src0_sel:WORD_1 src1_sel:DWORD
	v_and_b32_sdwa v46, v42, v41 dst_sel:DWORD dst_unused:UNUSED_PAD src0_sel:WORD_1 src1_sel:DWORD
	v_add3_u32 v1, v43, v1, s7
	v_add3_u32 v43, v45, v47, s7
	v_add3_u32 v44, v44, v48, s7
	v_add3_u32 v42, v42, v46, s7
	v_and_b32_e32 v43, 0xffff0000, v43
	v_and_b32_e32 v44, 0xffff0000, v44
	v_or_b32_sdwa v43, v43, v1 dst_sel:DWORD dst_unused:UNUSED_PAD src0_sel:DWORD src1_sel:WORD_1
	v_or_b32_sdwa v42, v44, v42 dst_sel:DWORD dst_unused:UNUSED_PAD src0_sel:DWORD src1_sel:WORD_1
	global_store_dwordx2 v[18:19], v[42:43], off offset:-2048
	v_mov_b32_e32 v46, v14
	v_mov_b32_e32 v47, v16
	v_mov_b32_e32 v16, v15
	v_pk_mul_f32 v[14:15], v[46:47], v[32:33] op_sel_hi:[1,0]
	v_pk_mul_f32 v[16:17], v[16:17], v[32:33] op_sel_hi:[1,0]
	s_nop 0
	v_mov_b32_e32 v46, v216
	v_mov_b32_e32 v47, v218
	v_mov_b32_e32 v44, v217
	v_pk_mul_f32 v[14:15], v[14:15], v[46:47]
	v_mov_b32_e32 v45, v219
	v_pk_mul_f32 v[16:17], v[16:17], v[44:45]
	v_and_b32_sdwa v1, v15, v41 dst_sel:DWORD dst_unused:UNUSED_PAD src0_sel:WORD_1 src1_sel:DWORD
	v_and_b32_sdwa v43, v17, v41 dst_sel:DWORD dst_unused:UNUSED_PAD src0_sel:WORD_1 src1_sel:DWORD
	v_and_b32_sdwa v44, v16, v41 dst_sel:DWORD dst_unused:UNUSED_PAD src0_sel:WORD_1 src1_sel:DWORD
	v_and_b32_sdwa v42, v14, v41 dst_sel:DWORD dst_unused:UNUSED_PAD src0_sel:WORD_1 src1_sel:DWORD
	v_add3_u32 v1, v15, v1, s7
	v_add3_u32 v15, v17, v43, s7
	v_add3_u32 v16, v16, v44, s7
	v_add3_u32 v14, v14, v42, s7
	v_and_b32_e32 v15, 0xffff0000, v15
	v_and_b32_e32 v16, 0xffff0000, v16
	v_or_b32_sdwa v15, v15, v1 dst_sel:DWORD dst_unused:UNUSED_PAD src0_sel:DWORD src1_sel:WORD_1
	v_or_b32_sdwa v14, v16, v14 dst_sel:DWORD dst_unused:UNUSED_PAD src0_sel:DWORD src1_sel:WORD_1
	global_store_dwordx2 v[18:19], v[14:15], off offset:-1536
	v_mov_b32_e32 v42, v10
	v_mov_b32_e32 v43, v12
	v_mov_b32_e32 v12, v11
	v_pk_mul_f32 v[10:11], v[42:43], v[32:33] op_sel_hi:[1,0]
	v_pk_mul_f32 v[12:13], v[12:13], v[32:33] op_sel_hi:[1,0]
	s_nop 0
	v_mov_b32_e32 v42, v220
	v_mov_b32_e32 v43, v222
	v_mov_b32_e32 v16, v221
	v_pk_mul_f32 v[10:11], v[10:11], v[42:43]
	v_mov_b32_e32 v17, v223
	v_pk_mul_f32 v[12:13], v[12:13], v[16:17]
	v_and_b32_sdwa v1, v11, v41 dst_sel:DWORD dst_unused:UNUSED_PAD src0_sel:WORD_1 src1_sel:DWORD
	v_and_b32_sdwa v15, v13, v41 dst_sel:DWORD dst_unused:UNUSED_PAD src0_sel:WORD_1 src1_sel:DWORD
	v_and_b32_sdwa v16, v12, v41 dst_sel:DWORD dst_unused:UNUSED_PAD src0_sel:WORD_1 src1_sel:DWORD
	v_and_b32_sdwa v14, v10, v41 dst_sel:DWORD dst_unused:UNUSED_PAD src0_sel:WORD_1 src1_sel:DWORD
	v_add3_u32 v1, v11, v1, s7
	v_add3_u32 v11, v13, v15, s7
	v_add3_u32 v12, v12, v16, s7
	v_add3_u32 v10, v10, v14, s7
	v_and_b32_e32 v11, 0xffff0000, v11
	v_and_b32_e32 v12, 0xffff0000, v12
	v_or_b32_sdwa v11, v11, v1 dst_sel:DWORD dst_unused:UNUSED_PAD src0_sel:DWORD src1_sel:WORD_1
	v_or_b32_sdwa v10, v12, v10 dst_sel:DWORD dst_unused:UNUSED_PAD src0_sel:DWORD src1_sel:WORD_1
	global_store_dwordx2 v[18:19], v[10:11], off offset:-1024
	v_mov_b32_e32 v14, v6
	v_mov_b32_e32 v15, v8
	v_mov_b32_e32 v8, v7
	v_pk_mul_f32 v[6:7], v[14:15], v[32:33] op_sel_hi:[1,0]
	v_pk_mul_f32 v[8:9], v[8:9], v[32:33] op_sel_hi:[1,0]
	s_nop 0
	v_mov_b32_e32 v14, v224
	v_mov_b32_e32 v15, v226
	v_mov_b32_e32 v12, v225
	v_pk_mul_f32 v[6:7], v[6:7], v[14:15]
	v_mov_b32_e32 v13, v227
	v_pk_mul_f32 v[8:9], v[8:9], v[12:13]
	v_and_b32_sdwa v1, v7, v41 dst_sel:DWORD dst_unused:UNUSED_PAD src0_sel:WORD_1 src1_sel:DWORD
	v_and_b32_sdwa v11, v9, v41 dst_sel:DWORD dst_unused:UNUSED_PAD src0_sel:WORD_1 src1_sel:DWORD
	v_and_b32_sdwa v12, v8, v41 dst_sel:DWORD dst_unused:UNUSED_PAD src0_sel:WORD_1 src1_sel:DWORD
	v_and_b32_sdwa v10, v6, v41 dst_sel:DWORD dst_unused:UNUSED_PAD src0_sel:WORD_1 src1_sel:DWORD
	v_add3_u32 v1, v7, v1, s7
	v_add3_u32 v7, v9, v11, s7
	v_add3_u32 v8, v8, v12, s7
	v_add3_u32 v6, v6, v10, s7
	v_and_b32_e32 v7, 0xffff0000, v7
	v_and_b32_e32 v8, 0xffff0000, v8
	v_or_b32_sdwa v7, v7, v1 dst_sel:DWORD dst_unused:UNUSED_PAD src0_sel:DWORD src1_sel:WORD_1
	v_or_b32_sdwa v6, v8, v6 dst_sel:DWORD dst_unused:UNUSED_PAD src0_sel:DWORD src1_sel:WORD_1
	global_store_dwordx2 v[18:19], v[6:7], off offset:-512
	v_mov_b32_e32 v10, v2
	v_mov_b32_e32 v11, v4
	v_mov_b32_e32 v4, v3
	v_pk_mul_f32 v[2:3], v[10:11], v[32:33] op_sel_hi:[1,0]
	v_pk_mul_f32 v[4:5], v[4:5], v[32:33] op_sel_hi:[1,0]
	s_nop 0
	v_mov_b32_e32 v10, v228
	v_mov_b32_e32 v11, v230
	v_mov_b32_e32 v8, v229
	v_pk_mul_f32 v[2:3], v[2:3], v[10:11]
	v_mov_b32_e32 v9, v231
	v_pk_mul_f32 v[4:5], v[4:5], v[8:9]
	v_and_b32_sdwa v1, v3, v41 dst_sel:DWORD dst_unused:UNUSED_PAD src0_sel:WORD_1 src1_sel:DWORD
	v_and_b32_sdwa v7, v5, v41 dst_sel:DWORD dst_unused:UNUSED_PAD src0_sel:WORD_1 src1_sel:DWORD
	v_and_b32_sdwa v8, v4, v41 dst_sel:DWORD dst_unused:UNUSED_PAD src0_sel:WORD_1 src1_sel:DWORD
	v_and_b32_sdwa v6, v2, v41 dst_sel:DWORD dst_unused:UNUSED_PAD src0_sel:WORD_1 src1_sel:DWORD
	v_add3_u32 v1, v3, v1, s7
	v_add3_u32 v3, v5, v7, s7
	v_add3_u32 v4, v4, v8, s7
	v_add3_u32 v2, v2, v6, s7
	v_and_b32_e32 v3, 0xffff0000, v3
	v_and_b32_e32 v4, 0xffff0000, v4
	v_or_b32_sdwa v3, v3, v1 dst_sel:DWORD dst_unused:UNUSED_PAD src0_sel:DWORD src1_sel:WORD_1
	v_or_b32_sdwa v2, v4, v2 dst_sel:DWORD dst_unused:UNUSED_PAD src0_sel:DWORD src1_sel:WORD_1
	global_store_dwordx2 v[18:19], v[2:3], off
	v_lshl_add_u64 v[18:19], v[18:19], 0, s[2:3]
	s_cbranch_scc0 .LBB0_227
